# rowpass A: the xor-32 step of both wave reductions uses v_permlane32_swap + add instead of a ds_bpermute round trip (same summation order)
# speedup vs baseline: 1.0039x; 1.0004x over previous
.LBB0_390:
	s_and_b32 s0, s14, 0x7ff
	s_cmpk_lt_i32 s14, 0x4000
	s_cselect_b32 s0, s0, s17
	v_lshl_or_b32 v152, s0, 9, v8
	v_lshl_add_u64 v[120:121], s[6:7], 0, v[152:153]
	global_load_dwordx2 v[100:101], v[120:121], off
	v_lshl_add_u64 v[118:119], s[8:9], 0, v[16:17]
	v_add_co_u32_e32 v118, vcc, 0xc701000, v118
	s_nop 1
	v_addc_co_u32_e32 v119, vcc, 0, v119, vcc
	global_load_ushort v102, v[118:119], off
	global_load_ushort v103, v[118:119], off offset:128
	global_load_ushort v104, v[118:119], off offset:256
	global_load_ushort v105, v[118:119], off offset:384
	global_load_ushort v106, v[118:119], off offset:512
	global_load_ushort v107, v[118:119], off offset:640
	global_load_ushort v108, v[118:119], off offset:768
	global_load_ushort v109, v[118:119], off offset:896
	global_load_ushort v110, v[118:119], off offset:1024
	global_load_ushort v111, v[118:119], off offset:1152
	global_load_ushort v112, v[118:119], off offset:1280
	global_load_ushort v113, v[118:119], off offset:1408
	global_load_ushort v114, v[118:119], off offset:1536
	global_load_ushort v115, v[118:119], off offset:1664
	global_load_ushort v116, v[118:119], off offset:1792
	global_load_ushort v117, v[118:119], off offset:1920
	v_lshl_add_u64 v[18:19], s[8:9], 0, v[14:15]
	v_add_co_u32_e32 v44, vcc, 0xc700000, v18
	s_cmpk_gt_i32 s14, 0x3fff
	s_nop 0
	v_addc_co_u32_e32 v45, vcc, 0, v19, vcc
	flat_load_dwordx4 v[0:3], v[44:45] offset:3072
	flat_load_dwordx4 v[4:7], v[44:45] offset:2048
	s_cselect_b64 s[10:11], -1, 0
	s_add_i32 s0, s14, 0xffffc000
	s_lshl_b64 s[4:5], s[0:1], 12
	s_add_u32 s12, s15, s4
	s_addc_u32 s13, s16, s5
	s_cmpk_lt_i32 s14, 0x4000
	v_lshlrev_b32_e32 v152, 2, v8
	s_waitcnt vmcnt(0) lgkmcnt(0)
	v_lshlrev_b32_e32 v20, 16, v0
	v_lshlrev_b32_e32 v50, 16, v4
	v_and_b32_e32 v21, 0xffff0000, v0
	v_and_b32_e32 v51, 0xffff0000, v4
	v_add_f32_e32 v0, 0, v50
	v_lshlrev_b32_e32 v46, 16, v5
	v_add_f32_e32 v0, v0, v51
	v_and_b32_e32 v47, 0xffff0000, v5
	v_add_f32_e32 v0, v0, v46
	v_lshlrev_b32_e32 v48, 16, v6
	v_add_f32_e32 v0, v0, v47
	v_and_b32_e32 v49, 0xffff0000, v6
	v_add_f32_e32 v0, v0, v48
	v_lshlrev_b32_e32 v28, 16, v7
	v_add_f32_e32 v0, v0, v49
	v_and_b32_e32 v29, 0xffff0000, v7
	v_add_f32_e32 v0, v0, v28
	v_add_f32_e32 v0, v0, v29
	v_add_f32_e32 v0, v0, v20
	v_lshlrev_b32_e32 v22, 16, v1
	v_add_f32_e32 v0, v0, v21
	v_and_b32_e32 v23, 0xffff0000, v1
	v_add_f32_e32 v0, v0, v22
	v_lshlrev_b32_e32 v24, 16, v2
	v_add_f32_e32 v0, v0, v23
	v_and_b32_e32 v25, 0xffff0000, v2
	v_add_f32_e32 v0, v0, v24
	v_lshlrev_b32_e32 v26, 16, v3
	v_add_f32_e32 v0, v0, v25
	v_and_b32_e32 v27, 0xffff0000, v3
	v_add_f32_e32 v0, v0, v26
	v_add_f32_e32 v0, v0, v27
	s_nop 1
	v_add_f32_dpp v0, v0, v0 quad_perm:[1,0,3,2] row_mask:0xf bank_mask:0xf
	s_nop 1
	v_add_f32_dpp v0, v0, v0 quad_perm:[2,3,0,1] row_mask:0xf bank_mask:0xf
	s_nop 1
	v_add_f32_dpp v0, v0, v0 row_half_mirror row_mask:0xf bank_mask:0xf
	s_nop 1
	v_add_f32_dpp v0, v0, v0 row_mirror row_mask:0xf bank_mask:0xf
	ds_bpermute_b32 v1, v33, v0
	s_waitcnt lgkmcnt(0)
	v_add_f32_e32 v35, v0, v1
	v_mov_b32_e32 v52, v35
	s_nop 1
	v_permlane32_swap_b32_e32 v35, v52
	v_mov_b32_e32 v0, v68
	v_mov_b32_e32 v1, v69
	v_mov_b32_e32 v2, v70
	v_mov_b32_e32 v3, v71
	v_mov_b32_e32 v36, v72
	v_mov_b32_e32 v37, v73
	v_mov_b32_e32 v38, v74
	v_mov_b32_e32 v39, v75
	v_mov_b32_e32 v4, v76
	v_mov_b32_e32 v5, v77
	v_mov_b32_e32 v6, v78
	v_mov_b32_e32 v7, v79
	v_mov_b32_e32 v40, v80
	v_mov_b32_e32 v41, v81
	v_mov_b32_e32 v42, v82
	v_mov_b32_e32 v43, v83
	v_add_f32_e32 v35, v35, v52
	v_mul_f32_e32 v52, 0x3a800000, v35
	v_pk_add_f32 v[50:51], v[50:51], v[52:53] op_sel_hi:[1,0] neg_lo:[0,1] neg_hi:[0,1]
	v_pk_add_f32 v[46:47], v[46:47], v[52:53] op_sel_hi:[1,0] neg_lo:[0,1] neg_hi:[0,1]
	v_pk_add_f32 v[54:55], v[28:29], v[52:53] op_sel_hi:[1,0] neg_lo:[0,1] neg_hi:[0,1]
	v_pk_mul_f32 v[28:29], v[50:51], v[50:51]
	v_pk_add_f32 v[48:49], v[48:49], v[52:53] op_sel_hi:[1,0] neg_lo:[0,1] neg_hi:[0,1]
	v_pk_add_f32 v[20:21], v[20:21], v[52:53] op_sel_hi:[1,0] neg_lo:[0,1] neg_hi:[0,1]
	v_pk_add_f32 v[22:23], v[22:23], v[52:53] op_sel_hi:[1,0] neg_lo:[0,1] neg_hi:[0,1]
	v_pk_add_f32 v[24:25], v[24:25], v[52:53] op_sel_hi:[1,0] neg_lo:[0,1] neg_hi:[0,1]
	v_pk_add_f32 v[26:27], v[26:27], v[52:53] op_sel_hi:[1,0] neg_lo:[0,1] neg_hi:[0,1]
	v_pk_mul_f32 v[52:53], v[46:47], v[46:47]
	v_add_f32_e32 v28, v28, v29
	v_add_f32_e32 v28, v52, v28
	v_pk_mul_f32 v[56:57], v[48:49], v[48:49]
	v_add_f32_e32 v28, v53, v28
	v_add_f32_e32 v28, v56, v28
	v_pk_mul_f32 v[58:59], v[54:55], v[54:55]
	v_add_f32_e32 v28, v57, v28
	v_add_f32_e32 v28, v58, v28
	v_pk_mul_f32 v[60:61], v[20:21], v[20:21]
	v_add_f32_e32 v28, v59, v28
	v_add_f32_e32 v28, v60, v28
	v_pk_mul_f32 v[62:63], v[22:23], v[22:23]
	v_add_f32_e32 v28, v61, v28
	v_add_f32_e32 v28, v62, v28
	v_pk_mul_f32 v[64:65], v[24:25], v[24:25]
	v_add_f32_e32 v28, v63, v28
	v_add_f32_e32 v28, v64, v28
	v_pk_mul_f32 v[66:67], v[26:27], v[26:27]
	v_add_f32_e32 v28, v65, v28
	v_add_f32_e32 v28, v66, v28
	v_add_f32_e32 v28, v67, v28
	s_nop 1
	v_add_f32_dpp v28, v28, v28 quad_perm:[1,0,3,2] row_mask:0xf bank_mask:0xf
	s_nop 1
	v_add_f32_dpp v28, v28, v28 quad_perm:[2,3,0,1] row_mask:0xf bank_mask:0xf
	s_nop 1
	v_add_f32_dpp v28, v28, v28 row_half_mirror row_mask:0xf bank_mask:0xf
	s_nop 1
	v_add_f32_dpp v28, v28, v28 row_mirror row_mask:0xf bank_mask:0xf
	ds_bpermute_b32 v29, v33, v28
	s_waitcnt lgkmcnt(0)
	v_add_f32_e32 v28, v28, v29
	v_mov_b32_e32 v29, v28
	s_nop 1
	v_permlane32_swap_b32_e32 v28, v29
	v_add_f32_e32 v28, v28, v29
	v_fmamk_f32 v28, v28, 0x3a800000, v183
	v_mul_f32_e32 v29, 0x4f800000, v28
	v_cmp_gt_f32_e32 vcc, s87, v28
	s_nop 1
	v_cndmask_b32_e32 v28, v28, v29, vcc
	v_sqrt_f32_e32 v29, v28
	s_nop 0
	v_add_u32_e32 v35, -1, v29
	v_add_u32_e32 v52, 1, v29
	v_fma_f32 v53, -v35, v29, v28
	v_fma_f32 v56, -v52, v29, v28
	v_cmp_ge_f32_e64 s[4:5], 0, v53
	s_nop 1
	v_cndmask_b32_e64 v29, v29, v35, s[4:5]
	v_cmp_lt_f32_e64 s[4:5], 0, v56
	s_nop 1
	v_cndmask_b32_e64 v29, v29, v52, s[4:5]
	v_mul_f32_e32 v35, 0x37800000, v29
	v_cndmask_b32_e32 v29, v29, v35, vcc
	v_cmp_class_f32_e32 vcc, v28, v189
	s_nop 1
	v_cndmask_b32_e32 v28, v29, v28, vcc
	v_div_scale_f32 v29, s[4:5], v28, v28, 1.0
	v_rcp_f32_e32 v35, v29
	v_div_scale_f32 v52, vcc, 1.0, v28, 1.0
	v_fma_f32 v53, -v29, v35, 1.0
	v_fmac_f32_e32 v35, v53, v35
	v_mul_f32_e32 v53, v52, v35
	v_fma_f32 v56, -v29, v53, v52
	v_fmac_f32_e32 v53, v56, v35
	v_fma_f32 v29, -v29, v53, v52
	v_div_fmas_f32 v29, v29, v35, v53
	v_div_fixup_f32 v28, v29, v28, 1.0
	v_pk_mul_f32 v[50:51], v[50:51], v[28:29] op_sel_hi:[1,0]
	v_pk_mul_f32 v[48:49], v[48:49], v[28:29] op_sel_hi:[1,0]
	v_pk_mul_f32 v[46:47], v[46:47], v[28:29] op_sel_hi:[1,0]
	v_pk_mul_f32 v[52:53], v[54:55], v[28:29] op_sel_hi:[1,0]
	v_pk_fma_f32 v[4:5], v[0:1], v[50:51], v[4:5]
	v_pk_fma_f32 v[0:1], v[36:37], v[48:49], v[40:41]
	v_pk_fma_f32 v[6:7], v[2:3], v[46:47], v[6:7]
	v_pk_fma_f32 v[2:3], v[38:39], v[52:53], v[42:43]
	v_cvt_pk_bf16_f32 v36, v4, v5
	v_cvt_pk_bf16_f32 v37, v6, v7
	v_cvt_pk_bf16_f32 v38, v0, v1
	v_cvt_pk_bf16_f32 v39, v2, v3
	flat_store_dwordx4 v[44:45], v[36:39] offset:2048
	s_cbranch_scc1 .LBB0_392
	s_nop 0
	v_lshl_add_u64 v[36:37], s[12:13], 0, v[152:153]
	flat_store_dwordx4 v[36:37], v[4:7] nt
	flat_store_dwordx4 v[36:37], v[0:3] offset:16 nt
